# MLA MFMA blocks reordered: P.V of the previous tile first, QK second, K fragments of the first QK k-steps prefetched from LDS during the P.V MFMAs (fragment allocator), on top of the DA pipelined + MF
# speedup vs baseline: 1.0240x; 1.0154x over previous
.LBB0_666:
	s_barrier
	s_setprio 3
	s_mov_b32 s12, s94
	s_mov_b32 s94, s8
	v_add_u32_e32 v250, s94, v185
	ds_read_b64_tr_b16 v[202:203], v250 offset:0
	ds_read_b64_tr_b16 v[204:205], v250 offset:0x800
	ds_read_b64_tr_b16 v[206:207], v250 offset:0x1000
	ds_read_b64_tr_b16 v[208:209], v250 offset:0x1800
	ds_read_b64_tr_b16 v[210:211], v250 offset:0x2000
	ds_read_b64_tr_b16 v[212:213], v250 offset:0x2800
	ds_read_b64_tr_b16 v[214:215], v250 offset:0x3000
	ds_read_b64_tr_b16 v[216:217], v250 offset:0x3800
	ds_read_b128 v[66:69], v189 offset:16384
	ds_read_b128 v[70:73], v189 offset:24576
	s_waitcnt lgkmcnt(8)
	v_mfma_f32_32x32x16_bf16 v[50:65], v[130:133], v[202:205], v[50:65]
	ds_read_b64_tr_b16 v[218:219], v250 offset:0x200
	ds_read_b64_tr_b16 v[220:221], v250 offset:0xa00
	s_waitcnt lgkmcnt(8)
	v_mfma_f32_32x32x16_bf16 v[50:65], v[126:129], v[206:209], v[50:65]
	ds_read_b64_tr_b16 v[222:223], v250 offset:0x1200
	ds_read_b64_tr_b16 v[224:225], v250 offset:0x1a00
	ds_read_b128 v[194:197], v190 offset:16384
	s_waitcnt lgkmcnt(9)
	v_mfma_f32_32x32x16_bf16 v[50:65], v[122:125], v[210:213], v[50:65]
	ds_read_b64_tr_b16 v[226:227], v250 offset:0x2200
	ds_read_b64_tr_b16 v[228:229], v250 offset:0x2a00
	s_waitcnt lgkmcnt(9)
	v_mfma_f32_32x32x16_bf16 v[50:65], v[118:121], v[214:217], v[50:65]
	ds_read_b64_tr_b16 v[230:231], v250 offset:0x3200
	ds_read_b64_tr_b16 v[232:233], v250 offset:0x3a00
	ds_read_b128 v[198:201], v190 offset:24576
	s_waitcnt lgkmcnt(8)
	v_mfma_f32_32x32x16_bf16 v[34:49], v[130:133], v[218:221], v[34:49]
	ds_read_b64_tr_b16 v[202:203], v250 offset:0x400
	ds_read_b64_tr_b16 v[204:205], v250 offset:0xc00
	s_waitcnt lgkmcnt(8)
	v_mfma_f32_32x32x16_bf16 v[34:49], v[126:129], v[222:225], v[34:49]
	ds_read_b64_tr_b16 v[206:207], v250 offset:0x1400
	ds_read_b64_tr_b16 v[208:209], v250 offset:0x1c00
	ds_read_b128 v[234:237], v191 offset:16384
	s_waitcnt lgkmcnt(8)
	v_mfma_f32_32x32x16_bf16 v[34:49], v[122:125], v[226:229], v[34:49]
	ds_read_b64_tr_b16 v[210:211], v250 offset:0x2400
	ds_read_b64_tr_b16 v[212:213], v250 offset:0x2c00
	s_waitcnt lgkmcnt(8)
	v_mfma_f32_32x32x16_bf16 v[34:49], v[118:121], v[230:233], v[34:49]
	ds_read_b64_tr_b16 v[214:215], v250 offset:0x3400
	ds_read_b64_tr_b16 v[216:217], v250 offset:0x3c00
	ds_read_b128 v[238:241], v191 offset:24576
	s_waitcnt lgkmcnt(8)
	v_mfma_f32_32x32x16_bf16 v[18:33], v[130:133], v[202:205], v[18:33]
	ds_read_b64_tr_b16 v[218:219], v250 offset:0x600
	ds_read_b64_tr_b16 v[220:221], v250 offset:0xe00
	s_waitcnt lgkmcnt(8)
	v_mfma_f32_32x32x16_bf16 v[18:33], v[126:129], v[206:209], v[18:33]
	ds_read_b64_tr_b16 v[222:223], v250 offset:0x1600
	ds_read_b64_tr_b16 v[224:225], v250 offset:0x1e00
	ds_read_b128 v[242:245], v192 offset:16384
	s_waitcnt lgkmcnt(8)
	v_mfma_f32_32x32x16_bf16 v[18:33], v[122:125], v[210:213], v[18:33]
	ds_read_b64_tr_b16 v[226:227], v250 offset:0x2600
	ds_read_b64_tr_b16 v[228:229], v250 offset:0x2e00
	s_waitcnt lgkmcnt(8)
	v_mfma_f32_32x32x16_bf16 v[18:33], v[118:121], v[214:217], v[18:33]
	ds_read_b64_tr_b16 v[230:231], v250 offset:0x3600
	ds_read_b64_tr_b16 v[232:233], v250 offset:0x3e00
	ds_read_b128 v[246:249], v192 offset:24576
	s_waitcnt lgkmcnt(8)
	v_mfma_f32_32x32x16_bf16 v[2:17], v[130:133], v[218:221], v[2:17]
	s_waitcnt lgkmcnt(6)
	v_mfma_f32_32x32x16_bf16 v[2:17], v[126:129], v[222:225], v[2:17]
	v_add_u32_e32 v202, v187, v168
	ds_read_b128 v[202:205], v202 offset:16384
	v_add_u32_e32 v206, v187, v168
	ds_read_b128 v[206:209], v206 offset:24576
	s_waitcnt lgkmcnt(5)
	v_mfma_f32_32x32x16_bf16 v[2:17], v[122:125], v[226:229], v[2:17]
	s_waitcnt lgkmcnt(3)
	v_mfma_f32_32x32x16_bf16 v[2:17], v[118:121], v[230:233], v[2:17]
	v_add_u32_e32 v210, v187, v170
	ds_read_b128 v[210:213], v210 offset:16384
	v_add_u32_e32 v214, v187, v170
	ds_read_b128 v[214:217], v214 offset:24576
	v_mfma_f32_32x32x16_bf16 v[82:97], v[66:69], v[114:117], 0
	v_mfma_f32_32x32x16_bf16 v[66:81], v[70:73], v[114:117], 0
	ds_read_b128 v[218:221], v159
	v_add_u32_e32 v222, v187, v172
	ds_read_b128 v[222:225], v222 offset:16384
	v_add_u32_e32 v226, v187, v172
	ds_read_b128 v[226:229], v226 offset:24576
	v_mfma_f32_32x32x16_bf16 v[82:97], v[194:197], v[110:113], v[82:97]
	v_mfma_f32_32x32x16_bf16 v[66:81], v[198:201], v[110:113], v[66:81]
	ds_read_b128 v[230:233], v159 offset:1024
	v_add_u32_e32 v194, v187, v174
	ds_read_b128 v[194:197], v194 offset:16384
	v_add_u32_e32 v198, v187, v174
	ds_read_b128 v[198:201], v198 offset:24576
	v_mfma_f32_32x32x16_bf16 v[82:97], v[234:237], v[106:109], v[82:97]
	v_mfma_f32_32x32x16_bf16 v[66:81], v[238:241], v[106:109], v[66:81]
	ds_read_b128 v[234:237], v159 offset:2048
	v_add_u32_e32 v238, v188, v177
	ds_read_b128 v[238:241], v238 offset:40960
	v_mfma_f32_32x32x16_bf16 v[82:97], v[242:245], v[102:105], v[82:97]
	s_waitcnt lgkmcnt(12)
	v_mfma_f32_32x32x16_bf16 v[66:81], v[246:249], v[102:105], v[66:81]
	v_add_u32_e32 v242, v188, v177
	ds_read_b128 v[242:245], v242 offset:45056
	ds_read_b128 v[246:249], v159 offset:3072
	s_waitcnt lgkmcnt(13)
	v_mfma_f32_32x32x16_bf16 v[82:97], v[202:205], v[98:101], v[82:97]
	s_waitcnt lgkmcnt(12)
	v_mfma_f32_32x32x16_bf16 v[66:81], v[206:209], v[98:101], v[66:81]
	v_add_u32_e32 v202, v188, v179
	ds_read_b128 v[202:205], v202 offset:40960
	v_add_u32_e32 v206, v188, v179
	ds_read_b128 v[206:209], v206 offset:45056
	s_waitcnt lgkmcnt(11)
	v_mfma_f32_32x32x16_bf16 v[82:97], v[210:213], v[218:221], v[82:97]
	v_mfma_f32_32x32x16_bf16 v[66:81], v[214:217], v[218:221], v[66:81]
	ds_read_b128 v[210:213], v159 offset:4096
	v_add_u32_e32 v214, v188, v181
	ds_read_b128 v[214:217], v214 offset:40960
	v_add_u32_e32 v218, v188, v181
	ds_read_b128 v[218:221], v218 offset:45056
	s_waitcnt lgkmcnt(11)
	v_mfma_f32_32x32x16_bf16 v[82:97], v[222:225], v[230:233], v[82:97]
	v_mfma_f32_32x32x16_bf16 v[66:81], v[226:229], v[230:233], v[66:81]
	ds_read_b128 v[222:225], v159 offset:5120
	v_add_u32_e32 v226, v188, v183
	ds_read_b128 v[226:229], v226 offset:40960
	v_add_u32_e32 v230, v188, v183
	ds_read_b128 v[230:233], v230 offset:45056
	s_waitcnt lgkmcnt(11)
	v_mfma_f32_32x32x16_bf16 v[82:97], v[194:197], v[234:237], v[82:97]
	v_mfma_f32_32x32x16_bf16 v[66:81], v[198:201], v[234:237], v[66:81]
	ds_read_b128 v[194:197], v159 offset:6144
	s_waitcnt lgkmcnt(9)
	v_mfma_f32_32x32x16_bf16 v[82:97], v[238:241], v[246:249], v[82:97]
	v_mfma_f32_32x32x16_bf16 v[66:81], v[242:245], v[246:249], v[66:81]
	s_waitcnt lgkmcnt(6)
	v_mfma_f32_32x32x16_bf16 v[82:97], v[202:205], v[210:213], v[82:97]
	v_mfma_f32_32x32x16_bf16 v[66:81], v[206:209], v[210:213], v[66:81]
	s_waitcnt lgkmcnt(3)
	v_mfma_f32_32x32x16_bf16 v[82:97], v[214:217], v[222:225], v[82:97]
	v_mfma_f32_32x32x16_bf16 v[66:81], v[218:221], v[222:225], v[66:81]
	s_waitcnt lgkmcnt(0)
	v_mfma_f32_32x32x16_bf16 v[82:97], v[226:229], v[194:197], v[82:97]
	v_mfma_f32_32x32x16_bf16 v[66:81], v[230:233], v[194:197], v[66:81]
	s_and_b64 vcc, exec, s[6:7]
	s_cbranch_vccnz .LBB0_668
	s_waitcnt vmcnt(0)

.LBB0_678:
	s_barrier
	s_setprio 3
	v_add_u32_e32 v252, s12, v185
	ds_read_b64_tr_b16 v[204:205], v252 offset:0
	ds_read_b64_tr_b16 v[206:207], v252 offset:0x800
	ds_read_b64_tr_b16 v[208:209], v252 offset:0x1000
	ds_read_b64_tr_b16 v[210:211], v252 offset:0x1800
	ds_read_b64_tr_b16 v[212:213], v252 offset:0x2000
	ds_read_b64_tr_b16 v[214:215], v252 offset:0x2800
	ds_read_b64_tr_b16 v[216:217], v252 offset:0x3000
	ds_read_b64_tr_b16 v[218:219], v252 offset:0x3800
	ds_read_b128 v[66:69], v161
	ds_read_b128 v[70:73], v161 offset:8192
	s_waitcnt lgkmcnt(8)
	v_mfma_f32_32x32x16_bf16 v[50:65], v[130:133], v[204:207], v[50:65]
	ds_read_b64_tr_b16 v[220:221], v252 offset:0x200
	ds_read_b64_tr_b16 v[222:223], v252 offset:0xa00
	s_waitcnt lgkmcnt(8)
	v_mfma_f32_32x32x16_bf16 v[50:65], v[126:129], v[208:211], v[50:65]
	ds_read_b64_tr_b16 v[224:225], v252 offset:0x1200
	ds_read_b64_tr_b16 v[226:227], v252 offset:0x1a00
	ds_read_b128 v[236:239], v163
	s_waitcnt lgkmcnt(9)
	v_mfma_f32_32x32x16_bf16 v[50:65], v[122:125], v[212:215], v[50:65]
	ds_read_b64_tr_b16 v[228:229], v252 offset:0x2200
	ds_read_b64_tr_b16 v[230:231], v252 offset:0x2a00
	s_waitcnt lgkmcnt(9)
	v_mfma_f32_32x32x16_bf16 v[50:65], v[118:121], v[216:219], v[50:65]
	ds_read_b64_tr_b16 v[232:233], v252 offset:0x3200
	ds_read_b64_tr_b16 v[234:235], v252 offset:0x3a00
	ds_read_b128 v[240:243], v163 offset:8192
	s_waitcnt lgkmcnt(8)
	v_mfma_f32_32x32x16_bf16 v[34:49], v[130:133], v[220:223], v[34:49]
	ds_read_b64_tr_b16 v[204:205], v252 offset:0x400
	ds_read_b64_tr_b16 v[206:207], v252 offset:0xc00
	s_waitcnt lgkmcnt(8)
	v_mfma_f32_32x32x16_bf16 v[34:49], v[126:129], v[224:227], v[34:49]
	ds_read_b64_tr_b16 v[208:209], v252 offset:0x1400
	ds_read_b64_tr_b16 v[210:211], v252 offset:0x1c00
	ds_read_b128 v[244:247], v165
	s_waitcnt lgkmcnt(8)
	v_mfma_f32_32x32x16_bf16 v[34:49], v[122:125], v[228:231], v[34:49]
	ds_read_b64_tr_b16 v[212:213], v252 offset:0x2400
	ds_read_b64_tr_b16 v[214:215], v252 offset:0x2c00
	s_waitcnt lgkmcnt(8)
	v_mfma_f32_32x32x16_bf16 v[34:49], v[118:121], v[232:235], v[34:49]
	ds_read_b64_tr_b16 v[216:217], v252 offset:0x3400
	ds_read_b64_tr_b16 v[218:219], v252 offset:0x3c00
	ds_read_b128 v[248:251], v165 offset:8192
	s_waitcnt lgkmcnt(8)
	v_mfma_f32_32x32x16_bf16 v[18:33], v[130:133], v[204:207], v[18:33]
	ds_read_b64_tr_b16 v[220:221], v252 offset:0x600
	ds_read_b64_tr_b16 v[222:223], v252 offset:0xe00
	s_waitcnt lgkmcnt(8)
	v_mfma_f32_32x32x16_bf16 v[18:33], v[126:129], v[208:211], v[18:33]
	ds_read_b64_tr_b16 v[224:225], v252 offset:0x1600
	ds_read_b64_tr_b16 v[226:227], v252 offset:0x1e00
	s_waitcnt lgkmcnt(7)
	v_mfma_f32_32x32x16_bf16 v[18:33], v[122:125], v[212:215], v[18:33]
	ds_read_b64_tr_b16 v[228:229], v252 offset:0x2600
	ds_read_b64_tr_b16 v[230:231], v252 offset:0x2e00
	s_waitcnt lgkmcnt(7)
	v_mfma_f32_32x32x16_bf16 v[18:33], v[118:121], v[216:219], v[18:33]
	ds_read_b64_tr_b16 v[232:233], v252 offset:0x3600
	ds_read_b64_tr_b16 v[234:235], v252 offset:0x3e00
	s_waitcnt lgkmcnt(6)
	v_mfma_f32_32x32x16_bf16 v[2:17], v[130:133], v[220:223], v[2:17]
	s_waitcnt lgkmcnt(4)
	v_mfma_f32_32x32x16_bf16 v[2:17], v[126:129], v[224:227], v[2:17]
	ds_read_b128 v[204:207], v167
	ds_read_b128 v[208:211], v167 offset:8192
	s_waitcnt lgkmcnt(4)
	v_mfma_f32_32x32x16_bf16 v[2:17], v[122:125], v[228:231], v[2:17]
	s_waitcnt lgkmcnt(2)
	v_mfma_f32_32x32x16_bf16 v[2:17], v[118:121], v[232:235], v[2:17]
	ds_read_b128 v[212:215], v169
	ds_read_b128 v[216:219], v169 offset:8192
	v_mfma_f32_32x32x16_bf16 v[82:97], v[66:69], v[114:117], 0
	v_mfma_f32_32x32x16_bf16 v[66:81], v[70:73], v[114:117], 0
	ds_read_b128 v[220:223], v171
	ds_read_b128 v[224:227], v171 offset:8192
	ds_read_b128 v[228:231], v159
	v_mfma_f32_32x32x16_bf16 v[82:97], v[236:239], v[110:113], v[82:97]
	v_mfma_f32_32x32x16_bf16 v[66:81], v[240:243], v[110:113], v[66:81]
	ds_read_b128 v[232:235], v173
	ds_read_b128 v[236:239], v173 offset:8192
	ds_read_b128 v[240:243], v159 offset:1024
	v_mfma_f32_32x32x16_bf16 v[82:97], v[244:247], v[106:109], v[82:97]
	v_mfma_f32_32x32x16_bf16 v[66:81], v[248:251], v[106:109], v[66:81]
	ds_read_b128 v[244:247], v175
	ds_read_b128 v[248:251], v175 offset:8192
	s_waitcnt lgkmcnt(11)
	v_mfma_f32_32x32x16_bf16 v[82:97], v[204:207], v[102:105], v[82:97]
	s_waitcnt lgkmcnt(10)
	v_mfma_f32_32x32x16_bf16 v[66:81], v[208:211], v[102:105], v[66:81]
	ds_read_b128 v[204:207], v159 offset:2048
	ds_read_b128 v[208:211], v178 offset:32768
	s_waitcnt lgkmcnt(11)
	v_mfma_f32_32x32x16_bf16 v[82:97], v[212:215], v[98:101], v[82:97]
	s_waitcnt lgkmcnt(10)
	v_mfma_f32_32x32x16_bf16 v[66:81], v[216:219], v[98:101], v[66:81]
	ds_read_b128 v[212:215], v178 offset:36864
	ds_read_b128 v[216:219], v159 offset:3072
	s_waitcnt lgkmcnt(9)
	v_mfma_f32_32x32x16_bf16 v[82:97], v[220:223], v[228:231], v[82:97]
	v_mfma_f32_32x32x16_bf16 v[66:81], v[224:227], v[228:231], v[66:81]
	ds_read_b128 v[220:223], v180 offset:32768
	ds_read_b128 v[224:227], v180 offset:36864
	ds_read_b128 v[228:231], v159 offset:4096
	s_waitcnt lgkmcnt(9)
	v_mfma_f32_32x32x16_bf16 v[82:97], v[232:235], v[240:243], v[82:97]
	v_mfma_f32_32x32x16_bf16 v[66:81], v[236:239], v[240:243], v[66:81]
	ds_read_b128 v[232:235], v182 offset:32768
	ds_read_b128 v[236:239], v182 offset:36864
	ds_read_b128 v[240:243], v159 offset:5120
	s_waitcnt lgkmcnt(9)
	v_mfma_f32_32x32x16_bf16 v[82:97], v[244:247], v[204:207], v[82:97]
	v_mfma_f32_32x32x16_bf16 v[66:81], v[248:251], v[204:207], v[66:81]
	ds_read_b128 v[244:247], v184 offset:32768
	ds_read_b128 v[248:251], v184 offset:36864
	ds_read_b128 v[204:207], v159 offset:6144
	s_waitcnt lgkmcnt(9)
	v_mfma_f32_32x32x16_bf16 v[82:97], v[208:211], v[216:219], v[82:97]
	v_mfma_f32_32x32x16_bf16 v[66:81], v[212:215], v[216:219], v[66:81]
	s_waitcnt lgkmcnt(6)
	v_mfma_f32_32x32x16_bf16 v[82:97], v[220:223], v[228:231], v[82:97]
	v_mfma_f32_32x32x16_bf16 v[66:81], v[224:227], v[228:231], v[66:81]
	s_waitcnt lgkmcnt(3)
	v_mfma_f32_32x32x16_bf16 v[82:97], v[232:235], v[240:243], v[82:97]
	v_mfma_f32_32x32x16_bf16 v[66:81], v[236:239], v[240:243], v[66:81]
	s_waitcnt lgkmcnt(0)
	v_mfma_f32_32x32x16_bf16 v[82:97], v[244:247], v[204:207], v[82:97]
	v_mfma_f32_32x32x16_bf16 v[66:81], v[248:251], v[204:207], v[66:81]
	s_and_b64 vcc, exec, s[6:7]
	s_cbranch_vccnz .LBB0_680
	s_waitcnt vmcnt(0)
